# prep and post tokens also mapped to the owning 8-block group, so zin->prep and post->out use the group barrier too (only prep->mixer and mixer->post stay grid-wide)
# speedup vs baseline: 1.0313x; 1.0069x over previous
.LBB0_471:
	s_mul_i32 s2, s34, 12
	v_readlane_b32 s20, v162, 12
	s_add_i32 s35, s2, 6
	v_readlane_b32 s21, v162, 13
	s_cmp_ge_i32 s35, s21
	v_readlane_b32 s22, v162, 14
	v_readlane_b32 s23, v162, 15
	s_cbranch_scc1 .LBB0_521
	s_waitcnt vmcnt(0)
	v_readlane_b32 s4, v163, 17
	v_readlane_b32 s5, v163, 18
	s_barrier
	v_lshrrev_b32_e32 v0, 6, v128
	v_readfirstlane_b32 s20, v0
	s_cmp_lg_u32 s20, 1
	s_cbranch_scc1 .Lxb3_ninv
	buffer_inv sc1
.Lxb3_ninv:
	s_barrier
	s_and_saveexec_b64 s[2:3], s[4:5]
	s_cbranch_execz .LBB0_520
	s_waitcnt vmcnt(0) lgkmcnt(0)
	v_readlane_b32 s20, v162, 62
	v_readlane_b32 s21, v164, 0
	v_readlane_b32 s22, v162, 63
	s_cmp_eq_u32 s20, 1
	s_cbranch_scc0 .Lxb3_glob
	s_and_b32 s4, s21, 15
	s_lshl_b32 s4, s4, 8
	s_bfe_u32 s5, s21, 0x20004
	s_lshl_b32 s5, s5, 5
	s_add_u32 s4, s4, s5
	s_add_u32 s4, s4, 0x480
	s_add_u32 s4, s84, s4
	s_addc_u32 s5, s85, 0
	s_add_u32 s22, s22, 1
	s_nop 1
	v_writelane_b32 v162, s22, 63
	s_lshl_b32 s22, s22, 3
	global_atomic_add v117, v129, s[4:5]
	s_mov_b32 s20, 0

.LBB0_523:
	s_andn2_b64 vcc, exec, s[2:3]
	s_cbranch_vccnz .LBB0_597
	v_readlane_b32 s10, v164, 0
	v_readlane_b32 s11, v162, 14
	v_lshrrev_b32_e32 v234, 6, v128
	v_and_b32_e32 v235, 63, v128
	v_readlane_b32 s16, v164, 43
	v_readlane_b32 s17, v164, 44
	v_readlane_b32 s18, v164, 47
	v_readlane_b32 s19, v164, 48
	v_readfirstlane_b32 s12, v234
	v_lshlrev_b32_e32 v232, 4, v235
	v_lshlrev_b32_e32 v233, 2, v235
	v_readlane_b32 s20, v164, 41
	v_readlane_b32 s21, v164, 42
	v_readlane_b32 s22, v164, 45
	v_readlane_b32 s23, v164, 46
	v_readlane_b32 s6, v164, 51
	v_readlane_b32 s7, v164, 52
	s_lshl_b32 s13, s10, 2
	s_add_u32 s13, s13, s12
	s_mul_i32 s13, s13, 5
	s_mul_i32 s14, s11, 20
	s_cmp_lg_u32 s11, 0x200
	s_cbranch_scc1 .Lgprep_tm_done
	s_and_b32 s4, s10, 7
	s_lshl_b32 s4, s4, 3
	s_bfe_u32 s32, s10, 0x30003
	s_or_b32 s4, s4, s32
	s_mul_i32 s4, s4, 0xa0
	s_lshr_b32 s32, s10, 6
	s_mul_i32 s32, s32, 20
	s_add_u32 s4, s4, s32
	s_mul_i32 s32, s12, 5
	s_add_u32 s13, s4, s32
	s_mov_b32 s14, 0x2800
.Lgprep_tm_done:
	s_lshl_b32 s4, s34, 16
	s_add_u32 s16, s16, s4
	s_addc_u32 s17, s17, 0
	s_add_u32 s18, s18, s4
	s_addc_u32 s19, s19, 0
	s_lshl_b32 s4, s34, 11
	s_add_u32 s20, s20, s4
	s_addc_u32 s21, s21, 0
	s_add_u32 s22, s22, s4
	s_addc_u32 s23, s23, 0
	s_lshl_b32 s4, s34, 10
	s_add_u32 s6, s6, s4
	s_addc_u32 s7, s7, 0
	global_load_dwordx4 v[30:33], v232, s[6:7]
	global_load_dwordx4 v[34:37], v232, s[20:21]
	global_load_dwordx4 v[38:41], v232, s[20:21] offset:1024
	global_load_dwordx4 v[42:45], v232, s[22:23]
	global_load_dwordx4 v[46:49], v232, s[22:23] offset:1024

.LBB0_801:
	s_andn2_b64 vcc, exec, s[2:3]
	s_cbranch_vccnz .LBB0_857
	v_readlane_b32 s10, v164, 0
	v_readlane_b32 s11, v162, 14
	v_lshrrev_b32_e32 v241, 6, v128
	v_and_b32_e32 v242, 63, v128
	v_readlane_b32 s16, v164, 49
	v_readlane_b32 s17, v164, 50
	v_readlane_b32 s18, v164, 57
	v_readlane_b32 s19, v164, 58
	v_readfirstlane_b32 s12, v241
	v_lshlrev_b32_e32 v248, 4, v242
	v_lshlrev_b32_e32 v249, 2, v242
	v_lshlrev_b32_e32 v250, 3, v242
	v_readlane_b32 s20, v164, 59
	v_readlane_b32 s21, v164, 60
	v_readlane_b32 s22, v164, 55
	v_readlane_b32 s23, v164, 56
	s_lshl_b32 s13, s10, 2
	s_add_u32 s13, s13, s12
	s_mul_i32 s13, s13, 5
	s_mul_i32 s14, s11, 20
	s_cmp_lg_u32 s11, 0x200
	s_cbranch_scc1 .Lgpost_tm_done
	s_and_b32 s4, s10, 7
	s_lshl_b32 s4, s4, 3
	s_bfe_u32 s32, s10, 0x30003
	s_or_b32 s4, s4, s32
	s_mul_i32 s4, s4, 0xa0
	s_lshr_b32 s32, s10, 6
	s_mul_i32 s32, s32, 20
	s_add_u32 s4, s4, s32
	s_mul_i32 s32, s12, 5
	s_add_u32 s13, s4, s32
	s_mov_b32 s14, 0x2800
.Lgpost_tm_done:
	s_lshl_b32 s4, s34, 10
	s_add_u32 s18, s18, s4
	s_addc_u32 s19, s19, 0
	s_add_u32 s20, s20, s4
	s_addc_u32 s21, s21, 0
	s_add_u32 s22, s22, s4
	s_addc_u32 s23, s23, 0
	s_lshl_b32 s4, s34, 16
	s_add_u32 s16, s16, s4
	s_addc_u32 s17, s17, 0
	global_load_dwordx4 v[110:113], v248, s[18:19]
	global_load_dwordx4 v[118:121], v248, s[20:21]
	global_load_dwordx4 v[122:125], v248, s[22:23]

.LBB0_807:
	s_or_b64 exec, exec, s[2:3]
	v_readlane_b32 s2, v162, 36
	v_readlane_b32 s20, v162, 12
	s_add_i32 s35, s2, 9
	v_readlane_b32 s21, v162, 13
	s_cmp_ge_i32 s35, s21
	v_readlane_b32 s22, v162, 14
	v_readlane_b32 s23, v162, 15
	s_cbranch_scc1 .LBB0_857
	s_waitcnt vmcnt(0)
	v_readlane_b32 s4, v163, 17
	v_readlane_b32 s5, v163, 18
	s_barrier
	v_lshrrev_b32_e32 v0, 6, v128
	v_readfirstlane_b32 s20, v0
	s_cmp_lg_u32 s20, 1
	s_cbranch_scc1 .Lxb6_ninv
	buffer_inv sc1
.Lxb6_ninv:
	s_barrier
	s_and_saveexec_b64 s[2:3], s[4:5]
	s_cbranch_execz .LBB0_856
	s_waitcnt vmcnt(0) lgkmcnt(0)
	v_readlane_b32 s20, v162, 62
	v_readlane_b32 s21, v164, 0
	v_readlane_b32 s22, v162, 63
	s_cmp_eq_u32 s20, 1
	s_cbranch_scc0 .Lxb6_glob
	s_and_b32 s4, s21, 15
	s_lshl_b32 s4, s4, 8
	s_bfe_u32 s5, s21, 0x20004
	s_lshl_b32 s5, s5, 5
	s_add_u32 s4, s4, s5
	s_add_u32 s4, s4, 0x480
	s_add_u32 s4, s84, s4
	s_addc_u32 s5, s85, 0
	s_add_u32 s22, s22, 1
	s_nop 1
	v_writelane_b32 v162, s22, 63
	s_lshl_b32 s22, s22, 3
	global_atomic_add v117, v129, s[4:5]
	s_mov_b32 s20, 0
